# conv module: y tile staged by one batch of LDS-DMA loads instead of 4 serialized register-staged rounds
# speedup vs baseline: 1.0014x; 1.0014x over previous
; __global__ void __launch_bounds__(512, 2) fwd_megakernel(Params Parg) {
;     ...
;         for (int tile = bid; tile < T / 32; tile += G) {
;             const int bt = tile / (L / 32), t0 = (tile % (L / 32)) * 32;
;             __syncthreads();
;             CONV_LOAD(tile);
;             __syncthreads();
.LBB0_1105:
	s_ashr_i32 s20, s43, 31
	s_lshr_b32 s20, s20, 23
	s_add_i32 s20, s43, s20
	s_ashr_i32 s38, s20, 9
	s_and_b32 s20, s20, 0x7fffe00
	s_sub_i32 s20, s43, s20
	s_lshl_b32 s44, s20, 5
	s_ashr_i32 s39, s38, 31
	v_mov_b32_e32 v90, v124
	s_add_i32 s45, s44, -15
	s_lshl_b64 s[20:21], s[38:39], 25
	s_barrier
	s_add_u32 s20, s4, s20
	v_lshlrev_b32_e32 v0, 4, v90
	s_addc_u32 s21, s5, s21
	v_and_b32_e32 v86, 0x7f0, v0
	v_lshl_add_u64 v[88:89], s[20:21], 0, v[86:87]
	v_add_u32_e32 v91, 0, v86
	v_lshl_add_u32 v92, v90, 2, v133
	v_readfirstlane_b32 s22, v124
	v_and_b32_e32 v1, 63, v124
	v_mov_b32_e32 v4, 0
	v_mov_b32_e32 v5, 0
	v_mov_b32_e32 v6, 0
	v_mov_b32_e32 v7, 0
	s_lshr_b32 s22, s22, 6
	v_lshlrev_b32_e32 v1, 4, v1
	s_lshr_b32 s23, s22, 1
	s_lshl_b32 s25, s22, 6
	s_add_i32 s24, s45, s23
	s_mov_b32 s26, s24
	s_ashr_i32 s27, s24, 31
	s_lshl_b64 s[26:27], s[26:27], 11
	s_add_u32 s26, s20, s26
	s_addc_u32 s27, s21, s27
	s_lshl_b32 s46, s22, 10
.Lconv_stage:
	s_cmp_ge_u32 s25, 0x1f00
	s_cbranch_scc1 .Lconv_stage_done
	s_cmp_lt_u32 s24, 0x4000
	s_cbranch_scc0 .Lconv_stage_zero
	s_mov_b32 m0, s46
	s_nop 0
	global_load_lds_dwordx4 v86, s[26:27]
	s_branch .Lconv_stage_next
.Lconv_stage_zero:
	v_add_u32_e32 v0, s46, v1
	ds_write_b128 v0, v[4:7]
.Lconv_stage_next:
	s_add_i32 s24, s24, 4
	s_add_u32 s26, s26, 0x2000
	s_addc_u32 s27, s27, 0
	s_addk_i32 s46, 0x2000
	s_addk_i32 s25, 0x200
	s_branch .Lconv_stage
.Lconv_stage_done:
	s_waitcnt vmcnt(0)
.LBB0_1123:
	s_lshl_b64 s[20:21], s[38:39], 14
	s_ashr_i32 s22, s44, 31
	s_add_u32 s26, s20, s44
	s_addc_u32 s23, s21, s22
	s_mov_b32 s22, 0
	s_mov_b64 s[20:21], -1
	s_waitcnt lgkmcnt(0)
	s_barrier
	s_waitcnt vmcnt(0)
	s_branch .LBB0_1125
